# DSA step 1 (indexer scores) loop rewritten by hand: head weights in registers, permlane32_swap instead of ds_bpermute, MFMAs of next row block issued ahead; one barrier instead of two in the unit prol
# speedup vs baseline: 1.0313x; 1.0094x over previous
.LBB0_186:
	s_ashr_i32 s2, s9, 4
	s_bfe_u32 s0, s9, 0x40004
	s_and_b32 s3, s2, 0xffffff0
	s_or_b32 s2, s2, 15
	s_and_b32 s4, s9, 15
	s_and_b32 s1, s9, 0x100
	s_sub_i32 s2, s2, s0
	s_or_b32 s0, s3, s0
	s_cmp_eq_u32 s1, 0
	s_cselect_b32 s0, s0, s2
	v_mov_b32_e32 v8, v221
	s_lshl_b32 s2, s0, 4
	v_writelane_b32 v254, s4, 30
	s_lshl_b32 s0, s4, 11
	s_add_i32 s6, s2, s0
	v_lshlrev_b32_e32 v0, 7, v8
	v_readlane_b32 s4, v254, 19
	v_bfe_u32 v4, v8, 3, 2
	v_bfe_u32 v3, v8, 5, 1
	v_and_b32_e32 v16, 0x380, v0
	v_readlane_b32 s5, v254, 20
	v_or_b32_e32 v4, s6, v4
	v_ashrrev_i32_e32 v5, 31, v4
	v_lshl_add_u64 v[0:1], s[4:5], 0, v[16:17]
	v_lshlrev_b32_e32 v16, 4, v3
	v_lshl_add_u64 v[0:1], v[0:1], 0, v[16:17]
	v_lshlrev_b64 v[6:7], 10, v[4:5]
	v_lshl_add_u64 v[6:7], v[0:1], 0, v[6:7]
	global_load_dwordx4 v[18:21], v[6:7], off
	global_load_dwordx4 v[22:25], v[6:7], off offset:32
	global_load_dwordx4 v[26:29], v[6:7], off offset:64
	global_load_dwordx4 v[30:33], v[6:7], off offset:96
	v_or_b32_e32 v6, 4, v4
	v_ashrrev_i32_e32 v7, 31, v6
	v_lshlrev_b64 v[6:7], 10, v[6:7]
	v_lshl_add_u64 v[6:7], v[0:1], 0, v[6:7]
	global_load_dwordx4 v[34:37], v[6:7], off
	global_load_dwordx4 v[38:41], v[6:7], off offset:32
	global_load_dwordx4 v[42:45], v[6:7], off offset:64
	global_load_dwordx4 v[46:49], v[6:7], off offset:96
	v_or_b32_e32 v6, 8, v4
	v_or_b32_e32 v4, 12, v4
	s_mov_b32 s4, s6
	v_ashrrev_i32_e32 v7, 31, v6
	v_ashrrev_i32_e32 v5, 31, v4
	v_writelane_b32 v254, s4, 31
	v_lshlrev_b64 v[6:7], 10, v[6:7]
	v_lshlrev_b64 v[4:5], 10, v[4:5]
	v_readlane_b32 s1, v253, 4
	v_and_b32_e32 v2, 31, v8
	v_writelane_b32 v254, s5, 32
	v_lshl_add_u64 v[6:7], v[0:1], 0, v[6:7]
	v_lshl_add_u64 v[0:1], v[0:1], 0, v[4:5]
	s_add_i32 s0, s0, s1
	global_load_dwordx4 v[50:53], v[6:7], off
	global_load_dwordx4 v[54:57], v[6:7], off offset:32
	global_load_dwordx4 v[58:61], v[6:7], off offset:64
	global_load_dwordx4 v[62:65], v[6:7], off offset:96
	global_load_dwordx4 v[66:69], v[0:1], off
	global_load_dwordx4 v[70:73], v[0:1], off offset:32
	global_load_dwordx4 v[74:77], v[0:1], off offset:64
	global_load_dwordx4 v[78:81], v[0:1], off offset:96
	v_or_b32_e32 v0, s0, v2
	v_mov_b32_e32 v1, v17
	v_readlane_b32 s0, v254, 21
	v_lshlrev_b64 v[0:1], 7, v[0:1]
	v_readlane_b32 s1, v254, 22
	s_nop 1
	v_lshl_add_u64 v[0:1], s[0:1], 0, v[0:1]
	v_lshl_add_u64 v[0:1], v[0:1], 0, v[16:17]
	global_load_dwordx4 v[98:101], v[0:1], off
	global_load_dwordx4 v[102:105], v[0:1], off offset:32
	global_load_dwordx4 v[106:109], v[0:1], off offset:64
	global_load_dwordx4 v[110:113], v[0:1], off offset:96
	v_readlane_b32 s0, v252, 7
	v_or_b32_e32 v0, s0, v8
	s_movk_i32 s0, 0x80
	v_cmp_gt_i32_e32 vcc, s0, v0
	s_and_saveexec_b64 s[0:1], vcc
	s_cbranch_execz .LBB0_188
	v_readlane_b32 s4, v254, 31
	v_readlane_b32 s5, v254, 32
	s_mov_b32 s6, s4
	s_ashr_i32 s7, s4, 31
	v_writelane_b32 v254, s4, 31
	v_ashrrev_i32_e32 v1, 31, v0
	s_nop 0
	v_writelane_b32 v254, s5, 32
	s_lshl_b64 s[4:5], s[6:7], 5
	v_readlane_b32 s3, v254, 25
	s_add_u32 s4, s3, s4
	v_readlane_b32 s3, v254, 26
	s_addc_u32 s5, s3, s5
	v_lshl_add_u64 v[4:5], v[0:1], 2, s[4:5]
	global_load_dword v1, v[4:5], off
	v_lshl_add_u32 v0, v0, 2, 0
	v_add_u32_e32 v0, 0x22000, v0
	s_waitcnt vmcnt(0)
	ds_write_b32 v0, v1
.LBB0_188:
	s_or_b64 exec, exec, s[0:1]
	s_waitcnt vmcnt(0)
	s_and_b32 s61, s2, 0xffffffc0
	s_add_i32 s61, s61, 64
	s_min_i32 s6, s61, 0x100
	s_ashr_i32 s7, s61, 5
	v_readlane_b32 s0, v253, 1
	s_cmp_ge_i32 s0, s7
	s_waitcnt lgkmcnt(0)
	s_barrier
	s_cbranch_scc1 .LBB0_225
	v_lshlrev_b32_e32 v0, 3, v3
	v_readlane_b32 s0, v254, 21
	v_lshlrev_b32_e32 v0, 1, v0
	v_mov_b32_e32 v1, v17
	v_readlane_b32 s1, v254, 22
	v_mov_b64_e32 v[82:83], v[98:99]
	v_mov_b64_e32 v[86:87], v[102:103]
	v_lshl_add_u64 v[114:115], s[0:1], 0, v[0:1]
	v_readlane_b32 s0, v254, 27
	s_and_b32 s0, s0, 15
	v_readlane_b32 s1, v253, 2
	s_lshl_b32 s0, s0, 11
	v_mov_b64_e32 v[90:91], v[106:107]
	v_lshl_add_u32 v118, v2, 2, s1
	v_readlane_b32 s1, v253, 5
	s_add_i32 s0, s1, s0
	v_mov_b64_e32 v[94:95], v[110:111]
	v_cmp_eq_u32_e64 s[4:5], 0, v3
	v_add_u32_e32 v116, s0, v2
	v_readlane_b32 s8, v253, 1
	v_mov_b64_e32 v[84:85], v[100:101]
	v_mov_b64_e32 v[88:89], v[104:105]
	v_mov_b64_e32 v[92:93], v[108:109]
	v_mov_b64_e32 v[96:97], v[112:113]
	v_add_u32_e32 v148, 0x22000, v16
	v_lshlrev_b32_e32 v150, 13, v3
	ds_read_b128 v[176:179], v148 offset:0
	ds_read_b128 v[180:183], v148 offset:32
	ds_read_b128 v[184:187], v148 offset:64
	ds_read_b128 v[188:191], v148 offset:96
	ds_read_b128 v[192:195], v148 offset:128
	ds_read_b128 v[196:199], v148 offset:160
	ds_read_b128 v[200:203], v148 offset:192
	ds_read_b128 v[204:207], v148 offset:224
	s_waitcnt lgkmcnt(0)
	ds_read_b128 v[208:211], v148 offset:256
	ds_read_b128 v[212:215], v148 offset:288
	ds_read_b128 v[232:235], v148 offset:320
	ds_read_b128 v[236:239], v148 offset:352
	ds_read_b128 v[240:243], v148 offset:384
	ds_read_b128 v[244:247], v148 offset:416
	ds_read_b128 v[248:251], v148 offset:448
	ds_read_b128 v[222:225], v148 offset:480
	s_branch .LBB0_191

.LBB0_193:
	s_waitcnt lgkmcnt(0)
	v_add_u32_e32 v149, v150, v118
	v_add_u32_e32 v148, 0x10000, v149
	v_mfma_f32_32x32x16_bf16 v[0:15], v[18:21], v[98:101], 0
	v_mfma_f32_32x32x16_bf16 v[0:15], v[22:25], v[102:105], v[0:15]
	v_mfma_f32_32x32x16_bf16 v[0:15], v[26:29], v[106:109], v[0:15]
	v_mfma_f32_32x32x16_bf16 v[0:15], v[30:33], v[110:113], v[0:15]
	v_mfma_f32_32x32x16_bf16 v[156:171], v[34:37], v[98:101], 0
	v_mfma_f32_32x32x16_bf16 v[156:171], v[38:41], v[102:105], v[156:171]
	v_mfma_f32_32x32x16_bf16 v[156:171], v[42:45], v[106:109], v[156:171]
	v_mfma_f32_32x32x16_bf16 v[156:171], v[46:49], v[110:113], v[156:171]
	s_nop 7
	v_max_f32_e32 v230, 0, v1
	v_max_f32_e32 v231, 0, v0
	v_mul_f32_e32 v172, v230, v177
	v_fmac_f32_e32 v172, v231, v176
	v_max_f32_e32 v230, 0, v2
	v_max_f32_e32 v231, 0, v3
	v_fmac_f32_e32 v172, v230, v178
	v_fmac_f32_e32 v172, v231, v179
	v_max_f32_e32 v230, 0, v5
	v_max_f32_e32 v231, 0, v4
	v_mul_f32_e32 v173, v230, v181
	v_fmac_f32_e32 v173, v231, v180
	v_max_f32_e32 v230, 0, v6
	v_max_f32_e32 v231, 0, v7
	v_fmac_f32_e32 v173, v230, v182
	v_fmac_f32_e32 v173, v231, v183
	v_max_f32_e32 v230, 0, v9
	v_max_f32_e32 v231, 0, v8
	v_mul_f32_e32 v155, v230, v185
	v_fmac_f32_e32 v155, v231, v184
	v_max_f32_e32 v230, 0, v10
	v_max_f32_e32 v231, 0, v11
	v_fmac_f32_e32 v155, v230, v186
	v_fmac_f32_e32 v155, v231, v187
	v_max_f32_e32 v230, 0, v13
	v_max_f32_e32 v231, 0, v12
	v_mul_f32_e32 v229, v230, v189
	v_fmac_f32_e32 v229, v231, v188
	v_max_f32_e32 v230, 0, v14
	v_max_f32_e32 v231, 0, v15
	v_fmac_f32_e32 v229, v230, v190
	v_fmac_f32_e32 v229, v231, v191
	s_nop 1
	v_permlane32_swap_b32_e32 v172, v173
	v_permlane32_swap_b32_e32 v155, v229
	v_add_f32_e32 v172, v172, v173
	ds_write_b32 v149, v172 offset:0
	v_add_f32_e32 v155, v155, v229
	ds_write_b32 v149, v155 offset:16384
	v_mfma_f32_32x32x16_bf16 v[0:15], v[50:53], v[98:101], 0
	v_mfma_f32_32x32x16_bf16 v[0:15], v[54:57], v[102:105], v[0:15]
	v_mfma_f32_32x32x16_bf16 v[0:15], v[58:61], v[106:109], v[0:15]
	v_mfma_f32_32x32x16_bf16 v[0:15], v[62:65], v[110:113], v[0:15]
	v_max_f32_e32 v230, 0, v157
	v_max_f32_e32 v231, 0, v156
	v_mul_f32_e32 v172, v230, v193
	v_fmac_f32_e32 v172, v231, v192
	v_max_f32_e32 v230, 0, v158
	v_max_f32_e32 v231, 0, v159
	v_fmac_f32_e32 v172, v230, v194
	v_fmac_f32_e32 v172, v231, v195
	v_max_f32_e32 v230, 0, v161
	v_max_f32_e32 v231, 0, v160
	v_mul_f32_e32 v173, v230, v197
	v_fmac_f32_e32 v173, v231, v196
	v_max_f32_e32 v230, 0, v162
	v_max_f32_e32 v231, 0, v163
	v_fmac_f32_e32 v173, v230, v198
	v_fmac_f32_e32 v173, v231, v199
	v_max_f32_e32 v230, 0, v165
	v_max_f32_e32 v231, 0, v164
	v_mul_f32_e32 v155, v230, v201
	v_fmac_f32_e32 v155, v231, v200
	v_max_f32_e32 v230, 0, v166
	v_max_f32_e32 v231, 0, v167
	v_fmac_f32_e32 v155, v230, v202
	v_fmac_f32_e32 v155, v231, v203
	v_max_f32_e32 v230, 0, v169
	v_max_f32_e32 v231, 0, v168
	v_mul_f32_e32 v229, v230, v205
	v_fmac_f32_e32 v229, v231, v204
	v_max_f32_e32 v230, 0, v170
	v_max_f32_e32 v231, 0, v171
	v_fmac_f32_e32 v229, v230, v206
	v_fmac_f32_e32 v229, v231, v207
	s_nop 1
	v_permlane32_swap_b32_e32 v172, v173
	v_permlane32_swap_b32_e32 v155, v229
	v_add_f32_e32 v172, v172, v173
	ds_write_b32 v149, v172 offset:32768
	v_add_f32_e32 v155, v155, v229
	ds_write_b32 v149, v155 offset:49152
	v_mfma_f32_32x32x16_bf16 v[156:171], v[66:69], v[98:101], 0
	v_mfma_f32_32x32x16_bf16 v[156:171], v[70:73], v[102:105], v[156:171]
	v_mfma_f32_32x32x16_bf16 v[156:171], v[74:77], v[106:109], v[156:171]
	v_mfma_f32_32x32x16_bf16 v[156:171], v[78:81], v[110:113], v[156:171]
	v_max_f32_e32 v230, 0, v1
	v_max_f32_e32 v231, 0, v0
	v_mul_f32_e32 v172, v230, v209
	v_fmac_f32_e32 v172, v231, v208
	v_max_f32_e32 v230, 0, v2
	v_max_f32_e32 v231, 0, v3
	v_fmac_f32_e32 v172, v230, v210
	v_fmac_f32_e32 v172, v231, v211
	v_max_f32_e32 v230, 0, v5
	v_max_f32_e32 v231, 0, v4
	v_mul_f32_e32 v173, v230, v213
	v_fmac_f32_e32 v173, v231, v212
	v_max_f32_e32 v230, 0, v6
	v_max_f32_e32 v231, 0, v7
	v_fmac_f32_e32 v173, v230, v214
	v_fmac_f32_e32 v173, v231, v215
	v_max_f32_e32 v230, 0, v9
	v_max_f32_e32 v231, 0, v8
	v_mul_f32_e32 v155, v230, v233
	v_fmac_f32_e32 v155, v231, v232
	v_max_f32_e32 v230, 0, v10
	v_max_f32_e32 v231, 0, v11
	v_fmac_f32_e32 v155, v230, v234
	v_fmac_f32_e32 v155, v231, v235
	v_max_f32_e32 v230, 0, v13
	v_max_f32_e32 v231, 0, v12
	v_mul_f32_e32 v229, v230, v237
	v_fmac_f32_e32 v229, v231, v236
	v_max_f32_e32 v230, 0, v14
	v_max_f32_e32 v231, 0, v15
	v_fmac_f32_e32 v229, v230, v238
	v_fmac_f32_e32 v229, v231, v239
	s_nop 1
	v_permlane32_swap_b32_e32 v172, v173
	v_permlane32_swap_b32_e32 v155, v229
	v_add_f32_e32 v172, v172, v173
	ds_write_b32 v148, v172 offset:0
	v_add_f32_e32 v155, v155, v229
	ds_write_b32 v148, v155 offset:16384
	v_max_f32_e32 v230, 0, v157
	v_max_f32_e32 v231, 0, v156
	v_mul_f32_e32 v172, v230, v241
	v_fmac_f32_e32 v172, v231, v240
	v_max_f32_e32 v230, 0, v158
	v_max_f32_e32 v231, 0, v159
	v_fmac_f32_e32 v172, v230, v242
	v_fmac_f32_e32 v172, v231, v243
	v_max_f32_e32 v230, 0, v161
	v_max_f32_e32 v231, 0, v160
	v_mul_f32_e32 v173, v230, v245
	v_fmac_f32_e32 v173, v231, v244
	v_max_f32_e32 v230, 0, v162
	v_max_f32_e32 v231, 0, v163
	v_fmac_f32_e32 v173, v230, v246
	v_fmac_f32_e32 v173, v231, v247
	v_max_f32_e32 v230, 0, v165
	v_max_f32_e32 v231, 0, v164
	v_mul_f32_e32 v155, v230, v249
	v_fmac_f32_e32 v155, v231, v248
	v_max_f32_e32 v230, 0, v166
	v_max_f32_e32 v231, 0, v167
	v_fmac_f32_e32 v155, v230, v250
	v_fmac_f32_e32 v155, v231, v251
	v_max_f32_e32 v230, 0, v169
	v_max_f32_e32 v231, 0, v168
	v_mul_f32_e32 v229, v230, v223
	v_fmac_f32_e32 v229, v231, v222
	v_max_f32_e32 v230, 0, v170
	v_max_f32_e32 v231, 0, v171
	v_fmac_f32_e32 v229, v230, v224
	v_fmac_f32_e32 v229, v231, v225
	s_nop 1
	v_permlane32_swap_b32_e32 v172, v173
	v_permlane32_swap_b32_e32 v155, v229
	v_add_f32_e32 v172, v172, v173
	ds_write_b32 v148, v172 offset:32768
	v_add_f32_e32 v155, v155, v229
	ds_write_b32 v148, v155 offset:49152
	s_branch .LBB0_190
